# kv-split attention: K fragment read placed right after the P.V MFMA in each gap (same schedule otherwise)
# speedup vs baseline: 1.0353x; 1.0061x over previous
; #define WAIT_BAR(N) asm volatile("s_waitcnt vmcnt(" #N ") lgkmcnt(0)\n\ts_barrier":::"memory")
;   #define RESC() do{ if(resc){ asm volatile("s_waitcnt lgkmcnt(0)":::"memory"); \
;       _Pragma("unroll") for(int d_=0;d_<2;++d_) _Pragma("unroll") for(int r=0;r<16;++r)o[d_][r]*=wsf[crow(r,hi)]; } }while(0)
;   #define ROT() do{sl_prev=sl_cur;sl_cur=sl_next;sl_next=sl_n2;sl_n2=(sl_n2==(NSLOT-1)*SLOTB)?0:sl_n2+SLOTB;}while(0)
; template<int MODE,int THRL,bool NOMAX> __device__ __forceinline__ void attn_unit(const bf16*Qs,const bf16*__restrict__ Ks,const bf16*__restrict__ Vs,bf16*Os,int S,int q0,float sink2,float slope2,float*ssq,char*shm,int tid_in){
;     ...
;   for(;t+5<NT;t+=2){
;     STEP(pB0,pB1,pA0,pA1,t,true,true,true);     WAIT_BAR(2); RESC(); ROT();
;     STEP(pA0,pA1,pB0,pB1,t+1,true,true,true);   RESC(); ROT();
;   }
.Lkvs_loop:
	s_waitcnt lgkmcnt(3)
	v_mfma_f32_32x32x16_bf16 v[98:113], v[178:181], v[146:149], 0
	v_add_u32_e32 v129, s15, v217
	ds_read_b64_tr_b16 v[210:211], v129 offset:40960
	v_add_f32_e32 v0, v66, v67
	v_add_f32_e32 v0, v68, v0
	v_add_f32_e32 v0, v69, v0
	v_cvt_pk_bf16_f32 v190, v66, v67
	v_cvt_pk_bf16_f32 v191, v68, v69
	v_mfma_f32_32x32x16_bf16 v[130:145], v[178:181], v[162:165], 0
	ds_read_b64_tr_b16 v[212:213], v129 offset:41472
	v_add_f32_e32 v0, v70, v0
	v_add_f32_e32 v0, v71, v0
	v_add_f32_e32 v0, v72, v0
	v_add_f32_e32 v0, v73, v0
	v_cvt_pk_bf16_f32 v192, v70, v71
	v_cvt_pk_bf16_f32 v193, v72, v73
	s_add_i32 s10, s15, s38
	s_mov_b32 m0, s10
	s_nop 0
	global_load_lds_dwordx4 v214, s[28:29]
	s_add_u32 s28, s28, 0x30000
	s_addc_u32 s29, s29, 0
	s_waitcnt lgkmcnt(4)
	v_mfma_f32_32x32x16_bf16 v[98:113], v[182:185], v[150:153], v[98:113]
	ds_read_b64_tr_b16 v[118:119], v129 offset:45056
	v_add_f32_e32 v0, v74, v0
	v_add_f32_e32 v0, v75, v0
	v_add_f32_e32 v0, v76, v0
	v_add_f32_e32 v0, v77, v0
	v_cvt_pk_bf16_f32 v194, v74, v75
	v_cvt_pk_bf16_f32 v195, v76, v77
	v_mfma_f32_32x32x16_bf16 v[130:145], v[182:185], v[166:169], v[130:145]
	ds_read_b64_tr_b16 v[120:121], v129 offset:45568
	v_add_f32_e32 v0, v78, v0
	v_add_f32_e32 v0, v79, v0
	v_add_f32_e32 v0, v80, v0
	v_add_f32_e32 v0, v81, v0
	v_add_f32_e32 v126, v126, v0
	v_cvt_pk_bf16_f32 v196, v78, v79
	v_cvt_pk_bf16_f32 v197, v80, v81
	s_waitcnt lgkmcnt(5)
	v_mfma_f32_32x32x16_bf16 v[98:113], v[186:189], v[154:157], v[98:113]
	ds_read_b64_tr_b16 v[122:123], v129 offset:41984
	v_add_f32_e32 v0, v82, v83
	v_add_f32_e32 v0, v84, v0
	v_add_f32_e32 v0, v85, v0
	v_cvt_pk_bf16_f32 v198, v82, v83
	v_cvt_pk_bf16_f32 v199, v84, v85
	v_mfma_f32_32x32x16_bf16 v[130:145], v[186:189], v[170:173], v[130:145]
	ds_read_b64_tr_b16 v[124:125], v129 offset:42496
	v_add_f32_e32 v0, v86, v0
	v_add_f32_e32 v0, v87, v0
	v_add_f32_e32 v0, v88, v0
	v_add_f32_e32 v0, v89, v0
	v_cvt_pk_bf16_f32 v200, v86, v87
	v_cvt_pk_bf16_f32 v201, v88, v89
	s_waitcnt lgkmcnt(6)
	v_mfma_f32_32x32x16_bf16 v[98:113], v[114:117], v[158:161], v[98:113]
	ds_read_b64_tr_b16 v[218:219], v129 offset:46080
	v_add_f32_e32 v0, v90, v0
	v_add_f32_e32 v0, v91, v0
	v_add_f32_e32 v0, v92, v0
	v_add_f32_e32 v0, v93, v0
	v_cvt_pk_bf16_f32 v206, v90, v91
	v_cvt_pk_bf16_f32 v207, v92, v93
	v_mfma_f32_32x32x16_bf16 v[130:145], v[114:117], v[174:177], v[130:145]
	ds_read_b64_tr_b16 v[220:221], v129 offset:46592
	v_add_f32_e32 v0, v94, v0
	v_add_f32_e32 v0, v95, v0
	v_add_f32_e32 v0, v96, v0
	v_add_f32_e32 v0, v97, v0
	v_add_f32_e32 v127, v127, v0
	v_cvt_pk_bf16_f32 v208, v94, v95
	v_cvt_pk_bf16_f32 v209, v96, v97
	s_waitcnt lgkmcnt(6)
	v_mfma_f32_32x32x16_bf16 v[2:17], v[190:193], v[210:213], v[2:17]
	v_add_u32_e32 v129, s44, v202
	v_exp_f32_e32 v98, v98
	v_exp_f32_e32 v99, v99
	v_exp_f32_e32 v100, v100
	v_exp_f32_e32 v101, v101
	s_waitcnt lgkmcnt(4)
	v_mfma_f32_32x32x16_bf16 v[18:33], v[190:193], v[118:121], v[18:33]
	ds_read_b128 v[178:181], v129
	v_exp_f32_e32 v102, v102
	v_exp_f32_e32 v103, v103
	v_exp_f32_e32 v104, v104
	v_exp_f32_e32 v105, v105
	s_add_i32 s10, s51, s39
	s_mov_b32 m0, s10
	s_nop 0
	global_load_lds_dwordx4 v215, s[36:37]
	s_add_u32 s36, s36, 0x30000
	s_addc_u32 s37, s37, 0
	v_mfma_f32_32x32x16_bf16 v[34:49], v[198:201], v[210:213], v[34:49]
	ds_read_b128 v[182:185], v129 offset:2048
	v_exp_f32_e32 v106, v106
	v_exp_f32_e32 v107, v107
	v_exp_f32_e32 v108, v108
	v_exp_f32_e32 v109, v109
	v_mfma_f32_32x32x16_bf16 v[50:65], v[198:201], v[118:121], v[50:65]
	ds_read_b128 v[186:189], v129 offset:4096
	v_exp_f32_e32 v110, v110
	v_exp_f32_e32 v111, v111
	v_exp_f32_e32 v112, v112
	v_exp_f32_e32 v113, v113
	s_waitcnt lgkmcnt(5)
	v_mfma_f32_32x32x16_bf16 v[2:17], v[194:197], v[122:125], v[2:17]
	ds_read_b128 v[114:117], v129 offset:6144
	v_exp_f32_e32 v130, v130
	v_exp_f32_e32 v131, v131
	v_exp_f32_e32 v132, v132
	v_exp_f32_e32 v133, v133
	s_waitcnt lgkmcnt(4)
	v_mfma_f32_32x32x16_bf16 v[18:33], v[194:197], v[218:221], v[18:33]
	v_exp_f32_e32 v134, v134
	v_exp_f32_e32 v135, v135
	v_exp_f32_e32 v136, v136
	v_exp_f32_e32 v137, v137
	v_mfma_f32_32x32x16_bf16 v[34:49], v[206:209], v[122:125], v[34:49]
	v_exp_f32_e32 v138, v138
	v_exp_f32_e32 v139, v139
	v_exp_f32_e32 v140, v140
	v_exp_f32_e32 v141, v141
	v_mfma_f32_32x32x16_bf16 v[50:65], v[206:209], v[218:221], v[50:65]
	v_exp_f32_e32 v142, v142
	v_exp_f32_e32 v143, v143
	v_exp_f32_e32 v144, v144
	v_exp_f32_e32 v145, v145
	s_mov_b32 s15, s14
	s_mov_b32 s14, s44
	s_mov_b32 s44, s51
	s_add_i32 s10, s51, 0x2000
	s_cmpk_lg_u32 s51, 0x8000
	s_cselect_b32 s51, s10, 0
	s_waitcnt vmcnt(2) lgkmcnt(0)
	s_barrier
; #define WAIT_BAR(N) asm volatile("s_waitcnt vmcnt(" #N ") lgkmcnt(0)\n\ts_barrier":::"memory")
;   #define RESC() do{ if(resc){ asm volatile("s_waitcnt lgkmcnt(0)":::"memory"); \
;       _Pragma("unroll") for(int d_=0;d_<2;++d_) _Pragma("unroll") for(int r=0;r<16;++r)o[d_][r]*=wsf[crow(r,hi)]; } }while(0)
;   #define ROT() do{sl_prev=sl_cur;sl_cur=sl_next;sl_next=sl_n2;sl_n2=(sl_n2==(NSLOT-1)*SLOTB)?0:sl_n2+SLOTB;}while(0)
; template<int MODE,int THRL,bool NOMAX> __device__ __forceinline__ void attn_unit(const bf16*Qs,const bf16*__restrict__ Ks,const bf16*__restrict__ Vs,bf16*Os,int S,int q0,float sink2,float slope2,float*ssq,char*shm,int tid_in){
;     ...
;   for(;t+5<NT;t+=2){
;     STEP(pB0,pB1,pA0,pA1,t,true,true,true);     WAIT_BAR(2); RESC(); ROT();
;     STEP(pA0,pA1,pB0,pB1,t+1,true,true,true);   RESC(); ROT();
;   }
	s_waitcnt lgkmcnt(3)
	v_mfma_f32_32x32x16_bf16 v[66:81], v[178:181], v[146:149], 0
	v_add_u32_e32 v129, s15, v217
	ds_read_b64_tr_b16 v[210:211], v129 offset:40960
	v_add_f32_e32 v0, v98, v99
	v_add_f32_e32 v0, v100, v0
	v_add_f32_e32 v0, v101, v0
	v_cvt_pk_bf16_f32 v190, v98, v99
	v_cvt_pk_bf16_f32 v191, v100, v101
	v_mfma_f32_32x32x16_bf16 v[82:97], v[178:181], v[162:165], 0
	ds_read_b64_tr_b16 v[212:213], v129 offset:41472
	v_add_f32_e32 v0, v102, v0
	v_add_f32_e32 v0, v103, v0
	v_add_f32_e32 v0, v104, v0
	v_add_f32_e32 v0, v105, v0
	v_cvt_pk_bf16_f32 v192, v102, v103
	v_cvt_pk_bf16_f32 v193, v104, v105
	s_add_i32 s10, s15, s38
	s_mov_b32 m0, s10
	s_nop 0
	global_load_lds_dwordx4 v214, s[28:29]
	s_add_u32 s28, s28, 0x30000
	s_addc_u32 s29, s29, 0
	s_waitcnt lgkmcnt(4)
	v_mfma_f32_32x32x16_bf16 v[66:81], v[182:185], v[150:153], v[66:81]
	ds_read_b64_tr_b16 v[118:119], v129 offset:45056
	v_add_f32_e32 v0, v106, v0
	v_add_f32_e32 v0, v107, v0
	v_add_f32_e32 v0, v108, v0
	v_add_f32_e32 v0, v109, v0
	v_cvt_pk_bf16_f32 v194, v106, v107
	v_cvt_pk_bf16_f32 v195, v108, v109
	v_mfma_f32_32x32x16_bf16 v[82:97], v[182:185], v[166:169], v[82:97]
	ds_read_b64_tr_b16 v[120:121], v129 offset:45568
	v_add_f32_e32 v0, v110, v0
	v_add_f32_e32 v0, v111, v0
	v_add_f32_e32 v0, v112, v0
	v_add_f32_e32 v0, v113, v0
	v_add_f32_e32 v126, v126, v0
	v_cvt_pk_bf16_f32 v196, v110, v111
	v_cvt_pk_bf16_f32 v197, v112, v113
	s_waitcnt lgkmcnt(5)
	v_mfma_f32_32x32x16_bf16 v[66:81], v[186:189], v[154:157], v[66:81]
	ds_read_b64_tr_b16 v[122:123], v129 offset:41984
	v_add_f32_e32 v0, v130, v131
	v_add_f32_e32 v0, v132, v0
	v_add_f32_e32 v0, v133, v0
	v_cvt_pk_bf16_f32 v198, v130, v131
	v_cvt_pk_bf16_f32 v199, v132, v133
	v_mfma_f32_32x32x16_bf16 v[82:97], v[186:189], v[170:173], v[82:97]
	ds_read_b64_tr_b16 v[124:125], v129 offset:42496
	v_add_f32_e32 v0, v134, v0
	v_add_f32_e32 v0, v135, v0
	v_add_f32_e32 v0, v136, v0
	v_add_f32_e32 v0, v137, v0
	v_cvt_pk_bf16_f32 v200, v134, v135
	v_cvt_pk_bf16_f32 v201, v136, v137
	s_waitcnt lgkmcnt(6)
	v_mfma_f32_32x32x16_bf16 v[66:81], v[114:117], v[158:161], v[66:81]
	ds_read_b64_tr_b16 v[218:219], v129 offset:46080
	v_add_f32_e32 v0, v138, v0
	v_add_f32_e32 v0, v139, v0
	v_add_f32_e32 v0, v140, v0
	v_add_f32_e32 v0, v141, v0
	v_cvt_pk_bf16_f32 v206, v138, v139
	v_cvt_pk_bf16_f32 v207, v140, v141
	v_mfma_f32_32x32x16_bf16 v[82:97], v[114:117], v[174:177], v[82:97]
	ds_read_b64_tr_b16 v[220:221], v129 offset:46592
	v_add_f32_e32 v0, v142, v0
	v_add_f32_e32 v0, v143, v0
	v_add_f32_e32 v0, v144, v0
	v_add_f32_e32 v0, v145, v0
	v_add_f32_e32 v127, v127, v0
	v_cvt_pk_bf16_f32 v208, v142, v143
	v_cvt_pk_bf16_f32 v209, v144, v145
	s_waitcnt lgkmcnt(6)
	v_mfma_f32_32x32x16_bf16 v[2:17], v[190:193], v[210:213], v[2:17]
	v_add_u32_e32 v129, s44, v202
	v_exp_f32_e32 v66, v66
	v_exp_f32_e32 v67, v67
	v_exp_f32_e32 v68, v68
	v_exp_f32_e32 v69, v69
	s_waitcnt lgkmcnt(4)
	v_mfma_f32_32x32x16_bf16 v[18:33], v[190:193], v[118:121], v[18:33]
	ds_read_b128 v[178:181], v129
	v_exp_f32_e32 v70, v70
	v_exp_f32_e32 v71, v71
	v_exp_f32_e32 v72, v72
	v_exp_f32_e32 v73, v73
	s_add_i32 s10, s51, s39
	s_mov_b32 m0, s10
	s_nop 0
	global_load_lds_dwordx4 v215, s[36:37]
	s_add_u32 s36, s36, 0x30000
	s_addc_u32 s37, s37, 0
	v_mfma_f32_32x32x16_bf16 v[34:49], v[198:201], v[210:213], v[34:49]
	ds_read_b128 v[182:185], v129 offset:2048
	v_exp_f32_e32 v74, v74
	v_exp_f32_e32 v75, v75
	v_exp_f32_e32 v76, v76
	v_exp_f32_e32 v77, v77
	v_mfma_f32_32x32x16_bf16 v[50:65], v[198:201], v[118:121], v[50:65]
	ds_read_b128 v[186:189], v129 offset:4096
	v_exp_f32_e32 v78, v78
	v_exp_f32_e32 v79, v79
	v_exp_f32_e32 v80, v80
	v_exp_f32_e32 v81, v81
	s_waitcnt lgkmcnt(5)
	v_mfma_f32_32x32x16_bf16 v[2:17], v[194:197], v[122:125], v[2:17]
	ds_read_b128 v[114:117], v129 offset:6144
	v_exp_f32_e32 v82, v82
	v_exp_f32_e32 v83, v83
	v_exp_f32_e32 v84, v84
	v_exp_f32_e32 v85, v85
	s_waitcnt lgkmcnt(4)
	v_mfma_f32_32x32x16_bf16 v[18:33], v[194:197], v[218:221], v[18:33]
	v_exp_f32_e32 v86, v86
	v_exp_f32_e32 v87, v87
	v_exp_f32_e32 v88, v88
	v_exp_f32_e32 v89, v89
	v_mfma_f32_32x32x16_bf16 v[34:49], v[206:209], v[122:125], v[34:49]
	v_exp_f32_e32 v90, v90
	v_exp_f32_e32 v91, v91
	v_exp_f32_e32 v92, v92
	v_exp_f32_e32 v93, v93
	v_mfma_f32_32x32x16_bf16 v[50:65], v[206:209], v[218:221], v[50:65]
	v_exp_f32_e32 v94, v94
	v_exp_f32_e32 v95, v95
	v_exp_f32_e32 v96, v96
	v_exp_f32_e32 v97, v97
	s_mov_b32 s15, s14
	s_mov_b32 s14, s44
	s_mov_b32 s44, s51
	s_add_i32 s10, s51, 0x2000
	s_cmpk_lg_u32 s51, 0x8000
	s_cselect_b32 s51, s10, 0
	s_add_i32 s18, s18, 2
	s_add_i32 s10, s18, 1
	s_cmp_lt_u32 s10, s40
	s_cbranch_scc1 .Lkvs_loop
; #define WAIT_BAR(N) asm volatile("s_waitcnt vmcnt(" #N ") lgkmcnt(0)\n\ts_barrier":::"memory")
;   #define RESC() do{ if(resc){ asm volatile("s_waitcnt lgkmcnt(0)":::"memory"); \
;       _Pragma("unroll") for(int d_=0;d_<2;++d_) _Pragma("unroll") for(int r=0;r<16;++r)o[d_][r]*=wsf[crow(r,hi)]; } }while(0)
;   #define ROT() do{sl_prev=sl_cur;sl_cur=sl_next;sl_next=sl_n2;sl_n2=(sl_n2==(NSLOT-1)*SLOTB)?0:sl_n2+SLOTB;}while(0)
;   #define ENDW(tt) do{ if((tt)+4<NT){WAIT_BAR(2);} else if((tt)+2<NT){WAIT_BAR(1);} else {WAIT_BAR(0);} }while(0)
; template<int MODE,int THRL,bool NOMAX> __device__ __forceinline__ void attn_unit(const bf16*Qs,const bf16*__restrict__ Ks,const bf16*__restrict__ Vs,bf16*Os,int S,int q0,float sink2,float slope2,float*ssq,char*shm,int tid_in){
;     ...
;   for(;t+1<NT;t+=2){
;     STEP(pB0,pB1,pA0,pA1,t,(t+4<NT),(t+2<NT),(t+1<NT));       ENDW(t);   RESC(); ROT();
;     STEP(pA0,pA1,pB0,pB1,t+1,(t+5<NT),(t+3<NT),(t+2<NT));     if(t+3>=NT){WAIT_BAR(0);} RESC(); ROT();
;   }
;   STEP(pB0,pB1,pA0,pA1,NT-1,false,false,false); RESC();
	s_waitcnt lgkmcnt(3)
	v_mfma_f32_32x32x16_bf16 v[98:113], v[178:181], v[146:149], 0
	v_add_u32_e32 v129, s15, v217
	ds_read_b64_tr_b16 v[210:211], v129 offset:40960
	v_add_f32_e32 v0, v66, v67
	v_add_f32_e32 v0, v68, v0
	v_add_f32_e32 v0, v69, v0
	v_cvt_pk_bf16_f32 v190, v66, v67
	v_cvt_pk_bf16_f32 v191, v68, v69
	v_mfma_f32_32x32x16_bf16 v[130:145], v[178:181], v[162:165], 0
	ds_read_b64_tr_b16 v[212:213], v129 offset:41472
	v_add_f32_e32 v0, v70, v0
	v_add_f32_e32 v0, v71, v0
	v_add_f32_e32 v0, v72, v0
	v_add_f32_e32 v0, v73, v0
	v_cvt_pk_bf16_f32 v192, v70, v71
	v_cvt_pk_bf16_f32 v193, v72, v73
	s_add_i32 s10, s15, s38
	s_mov_b32 m0, s10
	s_nop 0
	global_load_lds_dwordx4 v214, s[28:29]
	s_add_u32 s28, s28, 0x30000
	s_addc_u32 s29, s29, 0
	s_waitcnt lgkmcnt(4)
	v_mfma_f32_32x32x16_bf16 v[98:113], v[182:185], v[150:153], v[98:113]
	ds_read_b64_tr_b16 v[118:119], v129 offset:45056
	v_add_f32_e32 v0, v74, v0
	v_add_f32_e32 v0, v75, v0
	v_add_f32_e32 v0, v76, v0
	v_add_f32_e32 v0, v77, v0
	v_cvt_pk_bf16_f32 v194, v74, v75
	v_cvt_pk_bf16_f32 v195, v76, v77
	v_mfma_f32_32x32x16_bf16 v[130:145], v[182:185], v[166:169], v[130:145]
	ds_read_b64_tr_b16 v[120:121], v129 offset:45568
	v_add_f32_e32 v0, v78, v0
	v_add_f32_e32 v0, v79, v0
	v_add_f32_e32 v0, v80, v0
	v_add_f32_e32 v0, v81, v0
	v_add_f32_e32 v126, v126, v0
	v_cvt_pk_bf16_f32 v196, v78, v79
	v_cvt_pk_bf16_f32 v197, v80, v81
	s_waitcnt lgkmcnt(5)
	v_mfma_f32_32x32x16_bf16 v[98:113], v[186:189], v[154:157], v[98:113]
	ds_read_b64_tr_b16 v[122:123], v129 offset:41984
	v_add_f32_e32 v0, v82, v83
	v_add_f32_e32 v0, v84, v0
	v_add_f32_e32 v0, v85, v0
	v_cvt_pk_bf16_f32 v198, v82, v83
	v_cvt_pk_bf16_f32 v199, v84, v85
	v_mfma_f32_32x32x16_bf16 v[130:145], v[186:189], v[170:173], v[130:145]
	ds_read_b64_tr_b16 v[124:125], v129 offset:42496
	v_add_f32_e32 v0, v86, v0
	v_add_f32_e32 v0, v87, v0
	v_add_f32_e32 v0, v88, v0
	v_add_f32_e32 v0, v89, v0
	v_cvt_pk_bf16_f32 v200, v86, v87
	v_cvt_pk_bf16_f32 v201, v88, v89
	s_waitcnt lgkmcnt(6)
	v_mfma_f32_32x32x16_bf16 v[98:113], v[114:117], v[158:161], v[98:113]
	ds_read_b64_tr_b16 v[218:219], v129 offset:46080
	v_add_f32_e32 v0, v90, v0
	v_add_f32_e32 v0, v91, v0
	v_add_f32_e32 v0, v92, v0
	v_add_f32_e32 v0, v93, v0
	v_cvt_pk_bf16_f32 v206, v90, v91
	v_cvt_pk_bf16_f32 v207, v92, v93
	v_mfma_f32_32x32x16_bf16 v[130:145], v[114:117], v[174:177], v[130:145]
	ds_read_b64_tr_b16 v[220:221], v129 offset:46592
	v_add_f32_e32 v0, v94, v0
	v_add_f32_e32 v0, v95, v0
	v_add_f32_e32 v0, v96, v0
	v_add_f32_e32 v0, v97, v0
	v_add_f32_e32 v127, v127, v0
	v_cvt_pk_bf16_f32 v208, v94, v95
	v_cvt_pk_bf16_f32 v209, v96, v97
	s_waitcnt lgkmcnt(6)
	v_mfma_f32_32x32x16_bf16 v[2:17], v[190:193], v[210:213], v[2:17]
	v_add_u32_e32 v129, s44, v202
	v_exp_f32_e32 v98, v98
	v_exp_f32_e32 v99, v99
	v_exp_f32_e32 v100, v100
	v_exp_f32_e32 v101, v101
	s_waitcnt lgkmcnt(4)
	v_mfma_f32_32x32x16_bf16 v[18:33], v[190:193], v[118:121], v[18:33]
	ds_read_b128 v[178:181], v129
	v_exp_f32_e32 v102, v102
	v_exp_f32_e32 v103, v103
	v_exp_f32_e32 v104, v104
	v_exp_f32_e32 v105, v105
	s_add_i32 s10, s51, s39
	s_mov_b32 m0, s10
	s_nop 0
	global_load_lds_dwordx4 v215, s[36:37]
	s_add_u32 s36, s36, 0x30000
	s_addc_u32 s37, s37, 0
	v_mfma_f32_32x32x16_bf16 v[34:49], v[198:201], v[210:213], v[34:49]
	ds_read_b128 v[182:185], v129 offset:2048
	v_exp_f32_e32 v106, v106
	v_exp_f32_e32 v107, v107
	v_exp_f32_e32 v108, v108
	v_exp_f32_e32 v109, v109
	v_mfma_f32_32x32x16_bf16 v[50:65], v[198:201], v[118:121], v[50:65]
	ds_read_b128 v[186:189], v129 offset:4096
	v_exp_f32_e32 v110, v110
	v_exp_f32_e32 v111, v111
	v_exp_f32_e32 v112, v112
	v_exp_f32_e32 v113, v113
	s_waitcnt lgkmcnt(5)
	v_mfma_f32_32x32x16_bf16 v[2:17], v[194:197], v[122:125], v[2:17]
	ds_read_b128 v[114:117], v129 offset:6144
	v_exp_f32_e32 v130, v130
	v_exp_f32_e32 v131, v131
	v_exp_f32_e32 v132, v132
	v_exp_f32_e32 v133, v133
	s_waitcnt lgkmcnt(4)
	v_mfma_f32_32x32x16_bf16 v[18:33], v[194:197], v[218:221], v[18:33]
	v_exp_f32_e32 v134, v134
	v_exp_f32_e32 v135, v135
	v_exp_f32_e32 v136, v136
	v_exp_f32_e32 v137, v137
	v_mfma_f32_32x32x16_bf16 v[34:49], v[206:209], v[122:125], v[34:49]
	v_exp_f32_e32 v138, v138
	v_exp_f32_e32 v139, v139
	v_exp_f32_e32 v140, v140
	v_exp_f32_e32 v141, v141
	v_mfma_f32_32x32x16_bf16 v[50:65], v[206:209], v[218:221], v[50:65]
	v_exp_f32_e32 v142, v142
	v_exp_f32_e32 v143, v143
	v_exp_f32_e32 v144, v144
	v_exp_f32_e32 v145, v145
	s_mov_b32 s15, s14
	s_mov_b32 s14, s44
	s_mov_b32 s44, s51
	s_add_i32 s10, s51, 0x2000
	s_cmpk_lg_u32 s51, 0x8000
	s_cselect_b32 s51, s10, 0
	s_waitcnt vmcnt(2) lgkmcnt(0)
	s_barrier
; #define SBAR() __builtin_amdgcn_sched_barrier(0)
;   #define PKW(P,B) cvtpk_s(P[B],P[B+1])
;   #define LSUM(k) do{ if(LSM){ lsum=__builtin_amdgcn_mfma_f32_32x32x16_bf16(PAF(k),onesv,lsum,0,0,0); SBAR(); } }while(0)
; template<int MODE,int THRL,bool NOMAX> __device__ __forceinline__ void attn_unit(const bf16*Qs,const bf16*__restrict__ Ks,const bf16*__restrict__ Vs,bf16*Os,int S,int q0,float sink2,float slope2,float*ssq,char*shm,int tid_in){
;     ...
;   { float sacc=pB0[0]+pB0[1]; _Pragma("unroll") for(int r=2;r<16;++r)sacc+=pB0[r]; _Pragma("unroll") for(int r=0;r<16;++r)sacc+=pB1[r]; l_reg+=sacc;
;     pw0=(u32x4){PKW(pB0,0),PKW(pB0,2),PKW(pB0,4),PKW(pB0,6)};pw1=(u32x4){PKW(pB0,8),PKW(pB0,10),PKW(pB0,12),PKW(pB0,14)};pw2=(u32x4){PKW(pB1,0),PKW(pB1,2),PKW(pB1,4),PKW(pB1,6)};pw3=(u32x4){PKW(pB1,8),PKW(pB1,10),PKW(pB1,12),PKW(pB1,14)};
;     SBAR(); pv(o,vb0+sl_cur,PAF(0),PAF(1),PAF(2),PAF(3)); LSUM(0); LSUM(1); LSUM(2); LSUM(3); }
	v_add_u32_e32 v129, s15, v217
	ds_read_b64_tr_b16 v[210:211], v129 offset:40960
	ds_read_b64_tr_b16 v[212:213], v129 offset:41472
	ds_read_b64_tr_b16 v[118:119], v129 offset:45056
	ds_read_b64_tr_b16 v[120:121], v129 offset:45568
	ds_read_b64_tr_b16 v[122:123], v129 offset:41984
	ds_read_b64_tr_b16 v[124:125], v129 offset:42496
	ds_read_b64_tr_b16 v[218:219], v129 offset:46080
	ds_read_b64_tr_b16 v[220:221], v129 offset:46592
	v_add_f32_e32 v0, v98, v99
	v_add_f32_e32 v0, v100, v0
	v_add_f32_e32 v0, v101, v0
	v_add_f32_e32 v0, v102, v0
	v_add_f32_e32 v0, v103, v0
	v_add_f32_e32 v0, v104, v0
	v_add_f32_e32 v0, v105, v0
	v_add_f32_e32 v0, v106, v0
	v_add_f32_e32 v0, v107, v0
	v_add_f32_e32 v0, v108, v0
	v_add_f32_e32 v0, v109, v0
	v_add_f32_e32 v0, v110, v0
	v_add_f32_e32 v0, v111, v0
	v_add_f32_e32 v0, v112, v0
	v_add_f32_e32 v0, v113, v0
	v_add_f32_e32 v126, v126, v0
	v_cvt_pk_bf16_f32 v190, v98, v99
	v_cvt_pk_bf16_f32 v191, v100, v101
	v_cvt_pk_bf16_f32 v192, v102, v103
	v_cvt_pk_bf16_f32 v193, v104, v105
	v_cvt_pk_bf16_f32 v194, v106, v107
	v_cvt_pk_bf16_f32 v195, v108, v109
	v_cvt_pk_bf16_f32 v196, v110, v111
	v_cvt_pk_bf16_f32 v197, v112, v113
	v_add_f32_e32 v0, v130, v131
	v_add_f32_e32 v0, v132, v0
	v_add_f32_e32 v0, v133, v0
	v_add_f32_e32 v0, v134, v0
	v_add_f32_e32 v0, v135, v0
	v_add_f32_e32 v0, v136, v0
	v_add_f32_e32 v0, v137, v0
	v_add_f32_e32 v0, v138, v0
	v_add_f32_e32 v0, v139, v0
	v_add_f32_e32 v0, v140, v0
	v_add_f32_e32 v0, v141, v0
	v_add_f32_e32 v0, v142, v0
	v_add_f32_e32 v0, v143, v0
	v_add_f32_e32 v0, v144, v0
	v_add_f32_e32 v0, v145, v0
	v_add_f32_e32 v127, v127, v0
	v_cvt_pk_bf16_f32 v198, v130, v131
	v_cvt_pk_bf16_f32 v199, v132, v133
	v_cvt_pk_bf16_f32 v200, v134, v135
	v_cvt_pk_bf16_f32 v201, v136, v137
	v_cvt_pk_bf16_f32 v206, v138, v139
	v_cvt_pk_bf16_f32 v207, v140, v141
	v_cvt_pk_bf16_f32 v208, v142, v143
	v_cvt_pk_bf16_f32 v209, v144, v145
	s_nop 1
	s_waitcnt lgkmcnt(6)
	v_mfma_f32_32x32x16_bf16 v[2:17], v[190:193], v[210:213], v[2:17]
	s_waitcnt lgkmcnt(4)
	v_mfma_f32_32x32x16_bf16 v[18:33], v[190:193], v[118:121], v[18:33]
	v_mfma_f32_32x32x16_bf16 v[34:49], v[198:201], v[210:213], v[34:49]
	v_mfma_f32_32x32x16_bf16 v[50:65], v[198:201], v[118:121], v[50:65]
	s_waitcnt lgkmcnt(2)
	v_mfma_f32_32x32x16_bf16 v[2:17], v[194:197], v[122:125], v[2:17]
	s_waitcnt lgkmcnt(0)
	v_mfma_f32_32x32x16_bf16 v[18:33], v[194:197], v[218:221], v[18:33]
	v_mfma_f32_32x32x16_bf16 v[34:49], v[206:209], v[122:125], v[34:49]
	v_mfma_f32_32x32x16_bf16 v[50:65], v[206:209], v[218:221], v[50:65]
	s_waitcnt vmcnt(0) lgkmcnt(0)
	s_barrier
	v_and_b32_e32 v129, 63, v251
	v_lshlrev_b32_e32 v129, 2, v129
	s_xor_b32 s10, s30, 4
	s_lshl_b32 s11, s10, 13
	v_add_u32_e32 v186, s11, v129
	s_lshl_b32 s11, s10, 8
	s_add_i32 s11, s11, 0x10000
	v_add_u32_e32 v187, s11, v129
	s_lshl_b32 s11, s30, 13
	v_add_u32_e32 v114, s11, v129
	s_lshl_b32 s11, s30, 8
	s_add_i32 s11, s11, 0x10000
	v_add_u32_e32 v115, s11, v129
	s_cmp_eq_u32 s57, 0
	s_cbranch_scc1 .Lkvs_fin0
	ds_write_b32 v186, v2 offset:0
	ds_write_b32 v186, v3 offset:256
	ds_write_b32 v186, v4 offset:512
	ds_write_b32 v186, v5 offset:768
	ds_write_b32 v186, v6 offset:1024
	ds_write_b32 v186, v7 offset:1280
	ds_write_b32 v186, v8 offset:1536
	ds_write_b32 v186, v9 offset:1792
	ds_write_b32 v186, v10 offset:2048
	ds_write_b32 v186, v11 offset:2304
	ds_write_b32 v186, v12 offset:2560
	ds_write_b32 v186, v13 offset:2816
	ds_write_b32 v186, v14 offset:3072
	ds_write_b32 v186, v15 offset:3328
	ds_write_b32 v186, v16 offset:3584
	ds_write_b32 v186, v17 offset:3840
	ds_write_b32 v186, v18 offset:4096
	ds_write_b32 v186, v19 offset:4352
	ds_write_b32 v186, v20 offset:4608
	ds_write_b32 v186, v21 offset:4864
	ds_write_b32 v186, v22 offset:5120
	ds_write_b32 v186, v23 offset:5376
	ds_write_b32 v186, v24 offset:5632
	ds_write_b32 v186, v25 offset:5888
	ds_write_b32 v186, v26 offset:6144
	ds_write_b32 v186, v27 offset:6400
	ds_write_b32 v186, v28 offset:6656
	ds_write_b32 v186, v29 offset:6912
	ds_write_b32 v186, v30 offset:7168
	ds_write_b32 v186, v31 offset:7424
	ds_write_b32 v186, v32 offset:7680
	ds_write_b32 v186, v33 offset:7936
	ds_write_b32 v187, v126
	s_waitcnt lgkmcnt(0)
	s_barrier
	ds_read_b32 v66, v114 offset:0
	ds_read_b32 v67, v114 offset:256
	ds_read_b32 v68, v114 offset:512
	ds_read_b32 v69, v114 offset:768
	ds_read_b32 v70, v114 offset:1024
	ds_read_b32 v71, v114 offset:1280
	ds_read_b32 v72, v114 offset:1536
	ds_read_b32 v73, v114 offset:1792
	ds_read_b32 v74, v114 offset:2048
	ds_read_b32 v75, v114 offset:2304
	ds_read_b32 v76, v114 offset:2560
	ds_read_b32 v77, v114 offset:2816
	ds_read_b32 v78, v114 offset:3072
	ds_read_b32 v79, v114 offset:3328
	ds_read_b32 v80, v114 offset:3584
	ds_read_b32 v81, v114 offset:3840
	ds_read_b32 v82, v114 offset:4096
	ds_read_b32 v83, v114 offset:4352
	ds_read_b32 v84, v114 offset:4608
	ds_read_b32 v85, v114 offset:4864
	ds_read_b32 v86, v114 offset:5120
	ds_read_b32 v87, v114 offset:5376
	ds_read_b32 v88, v114 offset:5632
	ds_read_b32 v89, v114 offset:5888
	ds_read_b32 v90, v114 offset:6144
	ds_read_b32 v91, v114 offset:6400
	ds_read_b32 v92, v114 offset:6656
	ds_read_b32 v93, v114 offset:6912
	ds_read_b32 v94, v114 offset:7168
	ds_read_b32 v95, v114 offset:7424
	ds_read_b32 v96, v114 offset:7680
	ds_read_b32 v97, v114 offset:7936
	ds_read_b32 v178, v115
	s_waitcnt lgkmcnt(0)
; __device__ __forceinline__ int crow(int r,int hi){return (r&3)+8*(r>>2)+4*hi;}
; template<int MODE,int THRL,bool NOMAX> __device__ __forceinline__ void attn_unit(const bf16*Qs,const bf16*__restrict__ Ks,const bf16*__restrict__ Vs,bf16*Os,int S,int q0,float sink2,float slope2,float*ssq,char*shm,int tid_in){
;     ...
;   {auto rr=__builtin_amdgcn_permlane32_swap(__float_as_uint(l_reg),__float_as_uint(l_reg),false,false);l_reg=__uint_as_float(rr[0])+__uint_as_float(rr[1]);}
;   if(hi==0)wsf[32+r32]=l_reg;asm volatile("s_waitcnt lgkmcnt(0)":::"memory");
;   float rli[16];
;   #pragma unroll
;   for(int r=0;r<16;++r)rli[r]=LSM?__builtin_amdgcn_rcpf(lsum[r]):__builtin_amdgcn_rcpf(wsf[32+crow(r,hi)]);
;     ...
;   bf16*Ow=Os+(long)(q0+wid*QBLK)*OPITCH;
;   { bf16*stg=(bf16*)(shm+LDS_OST)+wid*2048;
;     #pragma unroll
;     for(int r=0;r<16;++r){const int orow=crow(r,hi);
;       #pragma unroll
;       for(int d0=0;d0<2;++d0)stg[orow*64+d0*32+r32]=__float2bfloat16(o[d0][r]*rli[r]);}
	v_add_f32_e32 v34, v34, v66
	v_add_f32_e32 v35, v35, v67
	v_add_f32_e32 v36, v36, v68
	v_add_f32_e32 v37, v37, v69
	v_add_f32_e32 v38, v38, v70
	v_add_f32_e32 v39, v39, v71
	v_add_f32_e32 v40, v40, v72
	v_add_f32_e32 v41, v41, v73
	v_add_f32_e32 v42, v42, v74
	v_add_f32_e32 v43, v43, v75
	v_add_f32_e32 v44, v44, v76
	v_add_f32_e32 v45, v45, v77
	v_add_f32_e32 v46, v46, v78
	v_add_f32_e32 v47, v47, v79
	v_add_f32_e32 v48, v48, v80
	v_add_f32_e32 v49, v49, v81
	v_add_f32_e32 v50, v50, v82
	v_add_f32_e32 v51, v51, v83
	v_add_f32_e32 v52, v52, v84
	v_add_f32_e32 v53, v53, v85
	v_add_f32_e32 v54, v54, v86
	v_add_f32_e32 v55, v55, v87
	v_add_f32_e32 v56, v56, v88
	v_add_f32_e32 v57, v57, v89
	v_add_f32_e32 v58, v58, v90
	v_add_f32_e32 v59, v59, v91
	v_add_f32_e32 v60, v60, v92
	v_add_f32_e32 v61, v61, v93
	v_add_f32_e32 v62, v62, v94
	v_add_f32_e32 v63, v63, v95
	v_add_f32_e32 v64, v64, v96
	v_add_f32_e32 v65, v65, v97
	v_add_f32_e32 v127, v127, v178
	v_and_b32_e32 v66, 31, v251
	v_and_b32_e32 v67, 63, v251
	v_lshrrev_b32_e32 v67, 5, v67
	s_lshl_b32 s10, s30, 8
	s_add_i32 s10, s10, 0x14000
	s_lshl_b32 s11, s30, 12
	s_add_i32 s11, s11, 0x14800
	v_and_b32_e32 v74, 63, v251
	v_lshrrev_b32_e32 v75, 3, v74
	v_and_b32_e32 v74, 7, v74
	v_lshlrev_b32_e32 v76, 4, v74
	v_lshl_add_u32 v76, v75, 7, v76
	v_add_u32_e32 v76, s11, v76
	v_lshlrev_b32_e32 v69, 9, v67
	v_lshl_add_u32 v69, v66, 1, v69
	v_add_u32_e32 v69, s11, v69
	v_lshl_add_u32 v68, v66, 2, s10
	v_mov_b32_e32 v70, v127
	s_nop 1
	v_permlane32_swap_b32_e32 v127, v70
	s_nop 1
	v_add_f32_e32 v70, v127, v70
	ds_write_b32 v68, v70 offset:128
	v_lshl_add_u32 v71, v67, 4, s10
	s_waitcnt lgkmcnt(0)
	ds_read_b128 v[82:85], v71 offset:128
	ds_read_b128 v[86:89], v71 offset:160
	ds_read_b128 v[90:93], v71 offset:192
	ds_read_b128 v[94:97], v71 offset:224
	s_waitcnt lgkmcnt(0)
	v_rcp_f32_e32 v82, v82
	v_rcp_f32_e32 v83, v83
	v_rcp_f32_e32 v84, v84
	v_rcp_f32_e32 v85, v85
	v_rcp_f32_e32 v86, v86
	v_rcp_f32_e32 v87, v87
	v_rcp_f32_e32 v88, v88
	v_rcp_f32_e32 v89, v89
	v_rcp_f32_e32 v90, v90
	v_rcp_f32_e32 v91, v91
	v_rcp_f32_e32 v92, v92
	v_rcp_f32_e32 v93, v93
	v_rcp_f32_e32 v94, v94
	v_rcp_f32_e32 v95, v95
	v_rcp_f32_e32 v96, v96
	v_rcp_f32_e32 v97, v97
	s_nop 0
	v_mul_f32_e32 v72, v34, v82
	v_cvt_pk_bf16_f32 v72, v72, v72
	ds_write_b16 v69, v72 offset:0
	v_mul_f32_e32 v73, v50, v82
	v_cvt_pk_bf16_f32 v73, v73, v73
	ds_write_b16 v69, v73 offset:64
	v_mul_f32_e32 v72, v35, v83
	v_cvt_pk_bf16_f32 v72, v72, v72
	ds_write_b16 v69, v72 offset:128
	v_mul_f32_e32 v73, v51, v83
	v_cvt_pk_bf16_f32 v73, v73, v73
	ds_write_b16 v69, v73 offset:192
	v_mul_f32_e32 v72, v36, v84
	v_cvt_pk_bf16_f32 v72, v72, v72
	ds_write_b16 v69, v72 offset:256
	v_mul_f32_e32 v73, v52, v84
	v_cvt_pk_bf16_f32 v73, v73, v73
	ds_write_b16 v69, v73 offset:320
	v_mul_f32_e32 v72, v37, v85
	v_cvt_pk_bf16_f32 v72, v72, v72
	ds_write_b16 v69, v72 offset:384
	v_mul_f32_e32 v73, v53, v85
	v_cvt_pk_bf16_f32 v73, v73, v73
	ds_write_b16 v69, v73 offset:448
	v_mul_f32_e32 v72, v38, v86
	v_cvt_pk_bf16_f32 v72, v72, v72
	ds_write_b16 v69, v72 offset:1024
	v_mul_f32_e32 v73, v54, v86
	v_cvt_pk_bf16_f32 v73, v73, v73
	ds_write_b16 v69, v73 offset:1088
	v_mul_f32_e32 v72, v39, v87
	v_cvt_pk_bf16_f32 v72, v72, v72
	ds_write_b16 v69, v72 offset:1152
	v_mul_f32_e32 v73, v55, v87
	v_cvt_pk_bf16_f32 v73, v73, v73
	ds_write_b16 v69, v73 offset:1216
	v_mul_f32_e32 v72, v40, v88
	v_cvt_pk_bf16_f32 v72, v72, v72
	ds_write_b16 v69, v72 offset:1280
	v_mul_f32_e32 v73, v56, v88
	v_cvt_pk_bf16_f32 v73, v73, v73
	ds_write_b16 v69, v73 offset:1344
	v_mul_f32_e32 v72, v41, v89
	v_cvt_pk_bf16_f32 v72, v72, v72
	ds_write_b16 v69, v72 offset:1408
	v_mul_f32_e32 v73, v57, v89
	v_cvt_pk_bf16_f32 v73, v73, v73
	ds_write_b16 v69, v73 offset:1472
	v_mul_f32_e32 v72, v42, v90
	v_cvt_pk_bf16_f32 v72, v72, v72
	ds_write_b16 v69, v72 offset:2048
	v_mul_f32_e32 v73, v58, v90
	v_cvt_pk_bf16_f32 v73, v73, v73
	ds_write_b16 v69, v73 offset:2112
	v_mul_f32_e32 v72, v43, v91
	v_cvt_pk_bf16_f32 v72, v72, v72
	ds_write_b16 v69, v72 offset:2176
	v_mul_f32_e32 v73, v59, v91
	v_cvt_pk_bf16_f32 v73, v73, v73
	ds_write_b16 v69, v73 offset:2240
	v_mul_f32_e32 v72, v44, v92
	v_cvt_pk_bf16_f32 v72, v72, v72
	ds_write_b16 v69, v72 offset:2304
	v_mul_f32_e32 v73, v60, v92
	v_cvt_pk_bf16_f32 v73, v73, v73
	ds_write_b16 v69, v73 offset:2368
	v_mul_f32_e32 v72, v45, v93
	v_cvt_pk_bf16_f32 v72, v72, v72
	ds_write_b16 v69, v72 offset:2432
	v_mul_f32_e32 v73, v61, v93
	v_cvt_pk_bf16_f32 v73, v73, v73
	ds_write_b16 v69, v73 offset:2496
	v_mul_f32_e32 v72, v46, v94
	v_cvt_pk_bf16_f32 v72, v72, v72
	ds_write_b16 v69, v72 offset:3072
	v_mul_f32_e32 v73, v62, v94
	v_cvt_pk_bf16_f32 v73, v73, v73
	ds_write_b16 v69, v73 offset:3136
	v_mul_f32_e32 v72, v47, v95
	v_cvt_pk_bf16_f32 v72, v72, v72
	ds_write_b16 v69, v72 offset:3200
	v_mul_f32_e32 v73, v63, v95
	v_cvt_pk_bf16_f32 v73, v73, v73
	ds_write_b16 v69, v73 offset:3264
	v_mul_f32_e32 v72, v48, v96
	v_cvt_pk_bf16_f32 v72, v72, v72
	ds_write_b16 v69, v72 offset:3328
	v_mul_f32_e32 v73, v64, v96
	v_cvt_pk_bf16_f32 v73, v73, v73
	ds_write_b16 v69, v73 offset:3392
	v_mul_f32_e32 v72, v49, v97
	v_cvt_pk_bf16_f32 v72, v72, v72
	ds_write_b16 v69, v72 offset:3456
	v_mul_f32_e32 v73, v65, v97
	v_cvt_pk_bf16_f32 v73, v73, v73
	ds_write_b16 v69, v73 offset:3520
	s_add_i32 s14, s4, 32
	s_mul_i32 s18, s14, 0x800
	s_mul_hi_i32 s19, s14, 0x800
	s_add_u32 s18, s48, s18
	s_addc_u32 s19, s49, s19
	s_mul_i32 s44, s14, 64
	s_mul_hi_i32 s45, s14, 64
	s_add_u32 s44, s26, s44
	s_addc_u32 s45, s27, s45
	v_lshlrev_b32_e32 v78, 11, v75
	v_lshl_add_u32 v78, v74, 4, v78
	v_lshlrev_b32_e32 v77, 6, v75
	v_cmp_eq_u32_e32 vcc, 0, v74
	s_waitcnt lgkmcnt(0)
; #define lane ({ int l_ = (int)__builtin_amdgcn_mbcnt_hi(~0u, __builtin_amdgcn_mbcnt_lo(~0u, 0u)); asm volatile("" : "+v"(l_)); l_; })
; template<int MODE,int THRL,bool NOMAX> __device__ __forceinline__ void attn_unit(const bf16*Qs,const bf16*__restrict__ Ks,const bf16*__restrict__ Vs,bf16*Os,int S,int q0,float sink2,float slope2,float*ssq,char*shm,int tid_in){
;     ...
;     asm volatile("s_waitcnt lgkmcnt(0)":::"memory");
;     #pragma unroll
;     for(int i=0;i<4;++i){const int row=i*8+(lane>>3),ch=lane&7; const u32x4 v=*(const u32x4*)(stg+row*64+ch*8); ATTN_STORE16(Ow+(long)row*OPITCH+ch*8,v);
;       float sq=0.f;
;       #pragma unroll
;       for(int k=0;k<4;++k){const float a=__uint_as_float(v[k]<<16),b=__uint_as_float(v[k]&0xffff0000u); sq+=a*a+b*b;}
;       sq+=__shfl_xor(sq,1); sq+=__shfl_xor(sq,2); sq+=__shfl_xor(sq,4);
;       if(ch==0)ssq[(long)(q0+wid*QBLK+row)*16]=sq;} }
	ds_read_b128 v[98:101], v76 offset:0
	ds_read_b128 v[102:105], v76 offset:1024
	ds_read_b128 v[106:109], v76 offset:2048
	ds_read_b128 v[110:113], v76 offset:3072
	s_waitcnt lgkmcnt(3)
	global_store_dwordx4 v78, v[98:101], s[18:19] offset:0
	v_and_b32_e32 v72, 0xffff0000, v98
	v_lshlrev_b32_e32 v73, 16, v98
	v_mul_f32_e32 v72, v72, v72
	v_fmac_f32_e32 v72, v73, v73
	v_mov_b32_e32 v130, v72
	v_and_b32_e32 v72, 0xffff0000, v99
	v_lshlrev_b32_e32 v73, 16, v99
	v_mul_f32_e32 v72, v72, v72
	v_fmac_f32_e32 v72, v73, v73
	v_add_f32_e32 v130, v130, v72
	v_and_b32_e32 v72, 0xffff0000, v100
	v_lshlrev_b32_e32 v73, 16, v100
	v_mul_f32_e32 v72, v72, v72
	v_fmac_f32_e32 v72, v73, v73
	v_add_f32_e32 v130, v72, v130
	v_and_b32_e32 v72, 0xffff0000, v101
	v_lshlrev_b32_e32 v73, 16, v101
	v_mul_f32_e32 v72, v72, v72
	v_fmac_f32_e32 v72, v73, v73
	v_add_f32_e32 v130, v72, v130
	v_add_u32_e32 v78, 0x4000, v78
	s_waitcnt lgkmcnt(2)
	global_store_dwordx4 v78, v[102:105], s[18:19]
	v_and_b32_e32 v72, 0xffff0000, v102
	v_lshlrev_b32_e32 v73, 16, v102
	v_mul_f32_e32 v72, v72, v72
	v_fmac_f32_e32 v72, v73, v73
	v_mov_b32_e32 v131, v72
	v_and_b32_e32 v72, 0xffff0000, v103
	v_lshlrev_b32_e32 v73, 16, v103
	v_mul_f32_e32 v72, v72, v72
	v_fmac_f32_e32 v72, v73, v73
	v_add_f32_e32 v131, v131, v72
	v_and_b32_e32 v72, 0xffff0000, v104
	v_lshlrev_b32_e32 v73, 16, v104
	v_mul_f32_e32 v72, v72, v72
	v_fmac_f32_e32 v72, v73, v73
	v_add_f32_e32 v131, v72, v131
	v_and_b32_e32 v72, 0xffff0000, v105
	v_lshlrev_b32_e32 v73, 16, v105
	v_mul_f32_e32 v72, v72, v72
	v_fmac_f32_e32 v72, v73, v73
	v_add_f32_e32 v131, v72, v131
	v_add_u32_e32 v78, 0x4000, v78
	s_waitcnt lgkmcnt(1)
	global_store_dwordx4 v78, v[106:109], s[18:19]
	v_and_b32_e32 v72, 0xffff0000, v106
	v_lshlrev_b32_e32 v73, 16, v106
	v_mul_f32_e32 v72, v72, v72
	v_fmac_f32_e32 v72, v73, v73
	v_mov_b32_e32 v132, v72
	v_and_b32_e32 v72, 0xffff0000, v107
	v_lshlrev_b32_e32 v73, 16, v107
	v_mul_f32_e32 v72, v72, v72
	v_fmac_f32_e32 v72, v73, v73
	v_add_f32_e32 v132, v132, v72
	v_and_b32_e32 v72, 0xffff0000, v108
	v_lshlrev_b32_e32 v73, 16, v108
	v_mul_f32_e32 v72, v72, v72
	v_fmac_f32_e32 v72, v73, v73
	v_add_f32_e32 v132, v72, v132
	v_and_b32_e32 v72, 0xffff0000, v109
	v_lshlrev_b32_e32 v73, 16, v109
	v_mul_f32_e32 v72, v72, v72
	v_fmac_f32_e32 v72, v73, v73
	v_add_f32_e32 v132, v72, v132
	v_add_u32_e32 v78, 0x4000, v78
	s_waitcnt lgkmcnt(0)
	global_store_dwordx4 v78, v[110:113], s[18:19]
	v_and_b32_e32 v72, 0xffff0000, v110
	v_lshlrev_b32_e32 v73, 16, v110
	v_mul_f32_e32 v72, v72, v72
	v_fmac_f32_e32 v72, v73, v73
	v_mov_b32_e32 v133, v72
	v_and_b32_e32 v72, 0xffff0000, v111
	v_lshlrev_b32_e32 v73, 16, v111
	v_mul_f32_e32 v72, v72, v72
	v_fmac_f32_e32 v72, v73, v73
	v_add_f32_e32 v133, v133, v72
	v_and_b32_e32 v72, 0xffff0000, v112
	v_lshlrev_b32_e32 v73, 16, v112
	v_mul_f32_e32 v72, v72, v72
	v_fmac_f32_e32 v72, v73, v73
	v_add_f32_e32 v133, v72, v133
	v_and_b32_e32 v72, 0xffff0000, v113
	v_lshlrev_b32_e32 v73, 16, v113
	v_mul_f32_e32 v72, v72, v72
	v_fmac_f32_e32 v72, v73, v73
	v_add_f32_e32 v133, v72, v133
	ds_bpermute_b32 v134, v239, v130
	ds_bpermute_b32 v135, v239, v131
	ds_bpermute_b32 v136, v239, v132
	ds_bpermute_b32 v137, v239, v133
	s_waitcnt lgkmcnt(0)
	v_add_f32_e32 v130, v130, v134
	v_add_f32_e32 v131, v131, v135
	v_add_f32_e32 v132, v132, v136
	v_add_f32_e32 v133, v133, v137
	ds_bpermute_b32 v134, v240, v130
	ds_bpermute_b32 v135, v240, v131
	ds_bpermute_b32 v136, v240, v132
	ds_bpermute_b32 v137, v240, v133
	s_waitcnt lgkmcnt(0)
	v_add_f32_e32 v130, v130, v134
	v_add_f32_e32 v131, v131, v135
	v_add_f32_e32 v132, v132, v136
	v_add_f32_e32 v133, v133, v137
	ds_bpermute_b32 v134, v241, v130
	ds_bpermute_b32 v135, v241, v131
	ds_bpermute_b32 v136, v241, v132
	ds_bpermute_b32 v137, v241, v133
	s_waitcnt lgkmcnt(0)
	v_add_f32_e32 v130, v130, v134
	v_add_f32_e32 v131, v131, v135
	v_add_f32_e32 v132, v132, v136
	v_add_f32_e32 v133, v133, v137
	s_nop 3
	s_and_saveexec_b64 s[10:11], vcc
	global_store_dword v77, v130, s[44:45]
	global_store_dword v77, v131, s[44:45] offset:512
	global_store_dword v77, v132, s[44:45] offset:1024
	global_store_dword v77, v133, s[44:45] offset:1536
	s_or_b64 exec, exec, s[10:11]
	s_branch .Lkvs_done
